# combine phase: loop software-pipelined two iterations deep (next element's six loads issued before the current element's math)
# speedup vs baseline: 1.0027x; 1.0027x over previous
; __device__ __forceinline__ unsigned cvt_pk_bf16(float lo, float hi) { unsigned r; asm volatile("v_cvt_pk_bf16_f32 %0, %1, %2" : "=v"(r) : "v"(lo), "v"(hi)); return r; }
; __device__ __forceinline__ float bf_lo(unsigned w) { return __uint_as_float(w << 16); }
; __device__ __forceinline__ float bf_hi(unsigned w) { return __uint_as_float(w & 0xffff0000u); }
; __device__ __forceinline__ void combine_phase(const bf16_t* __restrict__ og, const float* __restrict__ lse, bf16_t* __restrict__ dst, int G, int bid) {
;     ...
;     for (int idx = bid * NTHR + threadIdx.x; idx < SEQ * 256; idx += G * NTHR) {
;         const int t = idx >> 8, oc = idx & 255, h = oc >> 4;
;         const float l0 = lse[(size_t)t * 16 + h], l1 = lse[(size_t)SEQ * 16 + (size_t)t * 16 + h], l2 = lse[(size_t)2 * SEQ * 16 + (size_t)t * 16 + h];
;         const float mx = fmaxf(l0, fmaxf(l1, l2));
;         float w0 = __expf(l0 - mx), w1 = __expf(l1 - mx), w2 = __expf(l2 - mx);
;         const float inv = 1.0f / (w0 + w1 + w2); w0 *= inv; w1 *= inv; w2 *= inv;
;         const size_t off = (size_t)t * DM + oc * 8;
;         const u32x4 a = *(const u32x4*)(og + off), b = *(const u32x4*)(og + (size_t)SEQ * DM + off), c = *(const u32x4*)(og + (size_t)2 * SEQ * DM + off);
;         u32x4 w;
;         w.x = cvt_pk_bf16(w0 * bf_lo(a.x) + w1 * bf_lo(b.x) + w2 * bf_lo(c.x), w0 * bf_hi(a.x) + w1 * bf_hi(b.x) + w2 * bf_hi(c.x));
;         w.y = cvt_pk_bf16(w0 * bf_lo(a.y) + w1 * bf_lo(b.y) + w2 * bf_lo(c.y), w0 * bf_hi(a.y) + w1 * bf_hi(b.y) + w2 * bf_hi(c.y));
;         w.z = cvt_pk_bf16(w0 * bf_lo(a.z) + w1 * bf_lo(b.z) + w2 * bf_lo(c.z), w0 * bf_hi(a.z) + w1 * bf_hi(b.z) + w2 * bf_hi(c.z));
;         w.w = cvt_pk_bf16(w0 * bf_lo(a.w) + w1 * bf_lo(b.w) + w2 * bf_lo(c.w), w0 * bf_hi(a.w) + w1 * bf_hi(b.w) + w2 * bf_hi(c.w));
;         *(u32x4*)(dst + off) = w;
.LBB0_1292:
	s_cmp_lt_i32 s84, 15
	s_cselect_b64 s[2:3], -1, 0
	s_and_b64 s[2:3], s[2:3], s[0:1]
	s_andn2_b64 vcc, exec, s[2:3]
	s_cbranch_vccnz .LBB0_1301
	s_mov_b32 s0, 0x400000
	v_cmp_gt_i32_e32 vcc, s0, v225
	s_and_saveexec_b64 s[0:1], vcc
	v_readlane_b32 s14, v252, 11
	v_readlane_b32 s15, v252, 12
	s_cbranch_execz .LBB0_1296
	s_waitcnt lgkmcnt(0)
	s_add_u32 s4, s82, 0x1e680000
	s_addc_u32 s5, s83, 0
	s_add_u32 s6, s82, 0x22680000
	s_waitcnt vmcnt(2)
	v_bfe_u32 v0, v224, 4, 4
	v_mov_b32_e32 v2, 3
	s_addc_u32 s7, s83, 0
	s_lshl_b32 s10, s78, 9
	v_mov_b32_e32 v1, 0
	v_lshlrev_b32_sdwa v2, v2, v224 dst_sel:DWORD dst_unused:UNUSED_PAD src0_sel:DWORD src1_sel:BYTE_0
	s_mov_b64 s[8:9], 0
	v_lshlrev_b32_e32 v0, 2, v0
	s_mov_b32 s11, 0x3fffff
	s_cmpk_eq_u32 s78, 0x100
	s_cbranch_scc0 .LBB0_1295
	s_mov_b32 s99, 16
	v_ashrrev_i32_e32 v4, 8, v225
	v_ashrrev_i32_e32 v5, 31, v4
	v_lshlrev_b64 v[6:7], 6, v[4:5]
	v_add_u32_e32 v225, s10, v225
	v_lshl_add_u64 v[6:7], s[48:49], 0, v[6:7]
	v_lshlrev_b64 v[4:5], 12, v[4:5]
	v_lshl_add_u64 v[12:13], v[6:7], 0, v[0:1]
	v_lshl_or_b32 v4, v2, 1, v4
	v_add_co_u32_e32 v20, vcc, 0x100000, v12
	v_lshl_add_u64 v[8:9], s[4:5], 0, v[4:5]
	s_nop 0
	v_addc_co_u32_e32 v21, vcc, 0, v13, vcc
	v_lshl_add_u64 v[16:17], s[56:57], 0, v[4:5]
	v_lshl_add_u64 v[10:11], s[6:7], 0, v[4:5]
	v_lshl_add_u64 v[18:19], s[14:15], 0, v[4:5]
	global_load_dwordx4 v[4:7], v[8:9], off
	global_load_dword v3, v[12:13], off
	v_add_co_u32_e32 v22, vcc, 0x200000, v12
	global_load_dwordx4 v[8:11], v[10:11], off
	s_nop 0
	v_addc_co_u32_e32 v23, vcc, 0, v13, vcc
	global_load_dword v26, v[20:21], off
	global_load_dword v27, v[22:23], off
	global_load_dwordx4 v[12:15], v[16:17], off
.Lcmb_loop:
	v_ashrrev_i32_e32 v68, 8, v225
	v_ashrrev_i32_e32 v69, 31, v68
	v_lshlrev_b64 v[70:71], 6, v[68:69]
	v_add_u32_e32 v225, s10, v225
	v_lshl_add_u64 v[70:71], s[48:49], 0, v[70:71]
	v_lshlrev_b64 v[68:69], 12, v[68:69]
	v_lshl_add_u64 v[76:77], v[70:71], 0, v[0:1]
	v_lshl_or_b32 v68, v2, 1, v68
	v_add_co_u32_e32 v84, vcc, 0x100000, v76
	v_lshl_add_u64 v[72:73], s[4:5], 0, v[68:69]
	s_nop 0
	v_addc_co_u32_e32 v85, vcc, 0, v77, vcc
	v_lshl_add_u64 v[80:81], s[56:57], 0, v[68:69]
	v_lshl_add_u64 v[74:75], s[6:7], 0, v[68:69]
	v_lshl_add_u64 v[82:83], s[14:15], 0, v[68:69]
	global_load_dwordx4 v[68:71], v[72:73], off
	global_load_dword v67, v[76:77], off
	v_add_co_u32_e32 v86, vcc, 0x200000, v76
	global_load_dwordx4 v[72:75], v[74:75], off
	s_nop 0
	v_addc_co_u32_e32 v87, vcc, 0, v77, vcc
	global_load_dword v90, v[84:85], off
	global_load_dword v91, v[86:87], off
	global_load_dwordx4 v[76:79], v[80:81], off
	s_waitcnt vmcnt(6)
	v_lshlrev_b32_e32 v30, 16, v5
	v_and_b32_e32 v31, 0xffff0000, v5
	v_lshlrev_b32_e32 v34, 16, v7
	v_and_b32_e32 v35, 0xffff0000, v7
	v_lshlrev_b32_e32 v28, 16, v4
	v_and_b32_e32 v29, 0xffff0000, v4
	v_max3_f32 v36, v3, v26, v27
	v_lshlrev_b32_e32 v5, 16, v12
	v_and_b32_e32 v7, 0xffff0000, v12
	v_sub_f32_e32 v3, v3, v36
	v_sub_f32_e32 v12, v26, v36
	v_lshlrev_b32_e32 v32, 16, v6
	v_and_b32_e32 v33, 0xffff0000, v6
	v_lshlrev_b32_e32 v4, 16, v8
	v_and_b32_e32 v6, 0xffff0000, v8
	v_lshlrev_b32_e32 v8, 16, v9
	v_and_b32_e32 v16, 0xffff0000, v9
	v_lshlrev_b32_e32 v9, 16, v13
	v_and_b32_e32 v17, 0xffff0000, v13
	v_sub_f32_e32 v13, v27, v36
	v_mul_f32_e32 v3, 0x3fb8aa3b, v3
	v_mul_f32_e32 v12, 0x3fb8aa3b, v12
	v_lshlrev_b32_e32 v22, 16, v11
	v_and_b32_e32 v24, 0xffff0000, v11
	v_lshlrev_b32_e32 v21, 16, v14
	v_and_b32_e32 v11, 0xffff0000, v14
	v_mul_f32_e32 v14, 0x3fb8aa3b, v13
	v_exp_f32_e32 v13, v3
	v_exp_f32_e32 v3, v12
	v_exp_f32_e32 v12, v14
	v_lshlrev_b32_e32 v23, 16, v15
	v_and_b32_e32 v25, 0xffff0000, v15
	v_add_f32_e32 v14, v13, v3
	v_add_f32_e32 v14, v12, v14
	v_div_scale_f32 v15, s[12:13], v14, v14, 1.0
	v_rcp_f32_e32 v27, v15
	v_div_scale_f32 v26, vcc, 1.0, v14, 1.0
	v_lshlrev_b32_e32 v20, 16, v10
	v_fma_f32 v36, -v15, v27, 1.0
	v_fmac_f32_e32 v27, v36, v27
	v_mul_f32_e32 v36, v26, v27
	v_fma_f32 v37, -v15, v36, v26
	v_fmac_f32_e32 v36, v37, v27
	v_fma_f32 v15, -v15, v36, v26
	v_div_fmas_f32 v15, v15, v27, v36
	v_div_fixup_f32 v14, v15, v14, 1.0
	v_pk_mul_f32 v[12:13], v[12:13], v[14:15] op_sel_hi:[1,0]
	v_and_b32_e32 v10, 0xffff0000, v10
	v_mul_f32_e32 v3, v3, v14
	v_pk_mul_f32 v[4:5], v[12:13], v[4:5]
	v_pk_mul_f32 v[6:7], v[12:13], v[6:7]
	v_pk_mul_f32 v[8:9], v[12:13], v[8:9]
	v_pk_mul_f32 v[14:15], v[12:13], v[16:17]
	v_pk_mul_f32 v[16:17], v[12:13], v[20:21]
	v_pk_mul_f32 v[10:11], v[12:13], v[10:11]
	v_pk_mul_f32 v[20:21], v[12:13], v[22:23]
	v_pk_mul_f32 v[12:13], v[12:13], v[24:25]
	v_fma_f32 v5, v3, v28, v5
	v_fma_f32 v7, v3, v29, v7
	v_fma_f32 v9, v3, v30, v9
	v_fma_f32 v15, v3, v31, v15
	v_fma_f32 v17, v3, v32, v17
	v_fma_f32 v11, v3, v33, v11
	v_fma_f32 v21, v3, v34, v21
	v_fma_f32 v3, v3, v35, v13
	v_add_f32_e32 v4, v4, v5
	v_add_f32_e32 v5, v6, v7
	v_add_f32_e32 v6, v8, v9
	v_add_f32_e32 v7, v14, v15
	v_add_f32_e32 v8, v16, v17
	v_add_f32_e32 v9, v10, v11
	v_add_f32_e32 v10, v20, v21
	v_add_f32_e32 v3, v12, v3
	v_cvt_pk_bf16_f32 v4, v4, v5
	v_cvt_pk_bf16_f32 v5, v6, v7
	v_cvt_pk_bf16_f32 v6, v8, v9
	v_cvt_pk_bf16_f32 v7, v10, v3
	global_store_dwordx4 v[18:19], v[4:7], off
	s_sub_u32 s99, s99, 1
	s_cmp_eq_u32 s99, 0
	s_cbranch_scc1 .Lcmb_last
; __device__ __forceinline__ unsigned cvt_pk_bf16(float lo, float hi) { unsigned r; asm volatile("v_cvt_pk_bf16_f32 %0, %1, %2" : "=v"(r) : "v"(lo), "v"(hi)); return r; }
; __device__ __forceinline__ float bf_lo(unsigned w) { return __uint_as_float(w << 16); }
; __device__ __forceinline__ float bf_hi(unsigned w) { return __uint_as_float(w & 0xffff0000u); }
; __device__ __forceinline__ void combine_phase(const bf16_t* __restrict__ og, const float* __restrict__ lse, bf16_t* __restrict__ dst, int G, int bid) {
;     ...
;     for (int idx = bid * NTHR + threadIdx.x; idx < SEQ * 256; idx += G * NTHR) {
;         const int t = idx >> 8, oc = idx & 255, h = oc >> 4;
;         const float l0 = lse[(size_t)t * 16 + h], l1 = lse[(size_t)SEQ * 16 + (size_t)t * 16 + h], l2 = lse[(size_t)2 * SEQ * 16 + (size_t)t * 16 + h];
;         const float mx = fmaxf(l0, fmaxf(l1, l2));
;         float w0 = __expf(l0 - mx), w1 = __expf(l1 - mx), w2 = __expf(l2 - mx);
;         const float inv = 1.0f / (w0 + w1 + w2); w0 *= inv; w1 *= inv; w2 *= inv;
;         const size_t off = (size_t)t * DM + oc * 8;
;         const u32x4 a = *(const u32x4*)(og + off), b = *(const u32x4*)(og + (size_t)SEQ * DM + off), c = *(const u32x4*)(og + (size_t)2 * SEQ * DM + off);
;         u32x4 w;
;         w.x = cvt_pk_bf16(w0 * bf_lo(a.x) + w1 * bf_lo(b.x) + w2 * bf_lo(c.x), w0 * bf_hi(a.x) + w1 * bf_hi(b.x) + w2 * bf_hi(c.x));
;         w.y = cvt_pk_bf16(w0 * bf_lo(a.y) + w1 * bf_lo(b.y) + w2 * bf_lo(c.y), w0 * bf_hi(a.y) + w1 * bf_hi(b.y) + w2 * bf_hi(c.y));
;         w.z = cvt_pk_bf16(w0 * bf_lo(a.z) + w1 * bf_lo(b.z) + w2 * bf_lo(c.z), w0 * bf_hi(a.z) + w1 * bf_hi(b.z) + w2 * bf_hi(c.z));
;         w.w = cvt_pk_bf16(w0 * bf_lo(a.w) + w1 * bf_lo(b.w) + w2 * bf_lo(c.w), w0 * bf_hi(a.w) + w1 * bf_hi(b.w) + w2 * bf_hi(c.w));
;         *(u32x4*)(dst + off) = w;
	v_ashrrev_i32_e32 v4, 8, v225
	v_ashrrev_i32_e32 v5, 31, v4
	v_lshlrev_b64 v[6:7], 6, v[4:5]
	v_add_u32_e32 v225, s10, v225
	v_lshl_add_u64 v[6:7], s[48:49], 0, v[6:7]
	v_lshlrev_b64 v[4:5], 12, v[4:5]
	v_lshl_add_u64 v[12:13], v[6:7], 0, v[0:1]
	v_lshl_or_b32 v4, v2, 1, v4
	v_add_co_u32_e32 v20, vcc, 0x100000, v12
	v_lshl_add_u64 v[8:9], s[4:5], 0, v[4:5]
	s_nop 0
	v_addc_co_u32_e32 v21, vcc, 0, v13, vcc
	v_lshl_add_u64 v[16:17], s[56:57], 0, v[4:5]
	v_lshl_add_u64 v[10:11], s[6:7], 0, v[4:5]
	v_lshl_add_u64 v[18:19], s[14:15], 0, v[4:5]
	global_load_dwordx4 v[4:7], v[8:9], off
	global_load_dword v3, v[12:13], off
	v_add_co_u32_e32 v22, vcc, 0x200000, v12
	global_load_dwordx4 v[8:11], v[10:11], off
	s_nop 0
	v_addc_co_u32_e32 v23, vcc, 0, v13, vcc
	global_load_dword v26, v[20:21], off
	global_load_dword v27, v[22:23], off
	global_load_dwordx4 v[12:15], v[16:17], off
	s_waitcnt vmcnt(7)
	v_lshlrev_b32_e32 v94, 16, v69
	v_and_b32_e32 v95, 0xffff0000, v69
	v_lshlrev_b32_e32 v98, 16, v71
	v_and_b32_e32 v99, 0xffff0000, v71
	v_lshlrev_b32_e32 v92, 16, v68
	v_and_b32_e32 v93, 0xffff0000, v68
	v_max3_f32 v100, v67, v90, v91
	v_lshlrev_b32_e32 v69, 16, v76
	v_and_b32_e32 v71, 0xffff0000, v76
	v_sub_f32_e32 v67, v67, v100
	v_sub_f32_e32 v76, v90, v100
	v_lshlrev_b32_e32 v96, 16, v70
	v_and_b32_e32 v97, 0xffff0000, v70
	v_lshlrev_b32_e32 v68, 16, v72
	v_and_b32_e32 v70, 0xffff0000, v72
	v_lshlrev_b32_e32 v72, 16, v73
	v_and_b32_e32 v80, 0xffff0000, v73
	v_lshlrev_b32_e32 v73, 16, v77
	v_and_b32_e32 v81, 0xffff0000, v77
	v_sub_f32_e32 v77, v91, v100
	v_mul_f32_e32 v67, 0x3fb8aa3b, v67
	v_mul_f32_e32 v76, 0x3fb8aa3b, v76
	v_lshlrev_b32_e32 v86, 16, v75
	v_and_b32_e32 v88, 0xffff0000, v75
	v_lshlrev_b32_e32 v85, 16, v78
	v_and_b32_e32 v75, 0xffff0000, v78
	v_mul_f32_e32 v78, 0x3fb8aa3b, v77
	v_exp_f32_e32 v77, v67
	v_exp_f32_e32 v67, v76
	v_exp_f32_e32 v76, v78
	v_lshlrev_b32_e32 v87, 16, v79
	v_and_b32_e32 v89, 0xffff0000, v79
	v_add_f32_e32 v78, v77, v67
	v_add_f32_e32 v78, v76, v78
	v_div_scale_f32 v79, s[12:13], v78, v78, 1.0
	v_rcp_f32_e32 v91, v79
	v_div_scale_f32 v90, vcc, 1.0, v78, 1.0
	v_lshlrev_b32_e32 v84, 16, v74
	v_fma_f32 v100, -v79, v91, 1.0
	v_fmac_f32_e32 v91, v100, v91
	v_mul_f32_e32 v100, v90, v91
	v_fma_f32 v101, -v79, v100, v90
	v_fmac_f32_e32 v100, v101, v91
	v_fma_f32 v79, -v79, v100, v90
	v_div_fmas_f32 v79, v79, v91, v100
	v_div_fixup_f32 v78, v79, v78, 1.0
	v_pk_mul_f32 v[76:77], v[76:77], v[78:79] op_sel_hi:[1,0]
	v_and_b32_e32 v74, 0xffff0000, v74
	v_mul_f32_e32 v67, v67, v78
	v_pk_mul_f32 v[68:69], v[76:77], v[68:69]
	v_pk_mul_f32 v[70:71], v[76:77], v[70:71]
	v_pk_mul_f32 v[72:73], v[76:77], v[72:73]
	v_pk_mul_f32 v[78:79], v[76:77], v[80:81]
	v_pk_mul_f32 v[80:81], v[76:77], v[84:85]
	v_pk_mul_f32 v[74:75], v[76:77], v[74:75]
	v_pk_mul_f32 v[84:85], v[76:77], v[86:87]
	v_pk_mul_f32 v[76:77], v[76:77], v[88:89]
	v_fma_f32 v69, v67, v92, v69
	v_fma_f32 v71, v67, v93, v71
	v_fma_f32 v73, v67, v94, v73
	v_fma_f32 v79, v67, v95, v79
	v_fma_f32 v81, v67, v96, v81
	v_fma_f32 v75, v67, v97, v75
	v_fma_f32 v85, v67, v98, v85
	v_fma_f32 v67, v67, v99, v77
	v_add_f32_e32 v68, v68, v69
	v_add_f32_e32 v69, v70, v71
	v_add_f32_e32 v70, v72, v73
	v_add_f32_e32 v71, v78, v79
	v_add_f32_e32 v72, v80, v81
	v_add_f32_e32 v73, v74, v75
	v_add_f32_e32 v74, v84, v85
	v_add_f32_e32 v67, v76, v67
	v_cvt_pk_bf16_f32 v68, v68, v69
	v_cvt_pk_bf16_f32 v69, v70, v71
	v_cvt_pk_bf16_f32 v70, v72, v73
	v_cvt_pk_bf16_f32 v71, v74, v67
	global_store_dwordx4 v[82:83], v[68:71], off
	s_branch .Lcmb_loop
.Lcmb_last:
	s_waitcnt vmcnt(1)
	v_lshlrev_b32_e32 v94, 16, v69
	v_and_b32_e32 v95, 0xffff0000, v69
	v_lshlrev_b32_e32 v98, 16, v71
	v_and_b32_e32 v99, 0xffff0000, v71
	v_lshlrev_b32_e32 v92, 16, v68
	v_and_b32_e32 v93, 0xffff0000, v68
	v_max3_f32 v100, v67, v90, v91
	v_lshlrev_b32_e32 v69, 16, v76
	v_and_b32_e32 v71, 0xffff0000, v76
	v_sub_f32_e32 v67, v67, v100
	v_sub_f32_e32 v76, v90, v100
	v_lshlrev_b32_e32 v96, 16, v70
	v_and_b32_e32 v97, 0xffff0000, v70
	v_lshlrev_b32_e32 v68, 16, v72
	v_and_b32_e32 v70, 0xffff0000, v72
	v_lshlrev_b32_e32 v72, 16, v73
	v_and_b32_e32 v80, 0xffff0000, v73
	v_lshlrev_b32_e32 v73, 16, v77
	v_and_b32_e32 v81, 0xffff0000, v77
	v_sub_f32_e32 v77, v91, v100
	v_mul_f32_e32 v67, 0x3fb8aa3b, v67
	v_mul_f32_e32 v76, 0x3fb8aa3b, v76
	v_lshlrev_b32_e32 v86, 16, v75
	v_and_b32_e32 v88, 0xffff0000, v75
	v_lshlrev_b32_e32 v85, 16, v78
	v_and_b32_e32 v75, 0xffff0000, v78
	v_mul_f32_e32 v78, 0x3fb8aa3b, v77
	v_exp_f32_e32 v77, v67
	v_exp_f32_e32 v67, v76
	v_exp_f32_e32 v76, v78
	v_lshlrev_b32_e32 v87, 16, v79
	v_and_b32_e32 v89, 0xffff0000, v79
	v_add_f32_e32 v78, v77, v67
	v_add_f32_e32 v78, v76, v78
	v_div_scale_f32 v79, s[12:13], v78, v78, 1.0
	v_rcp_f32_e32 v91, v79
	v_div_scale_f32 v90, vcc, 1.0, v78, 1.0
	v_lshlrev_b32_e32 v84, 16, v74
	v_fma_f32 v100, -v79, v91, 1.0
	v_fmac_f32_e32 v91, v100, v91
	v_mul_f32_e32 v100, v90, v91
	v_fma_f32 v101, -v79, v100, v90
	v_fmac_f32_e32 v100, v101, v91
	v_fma_f32 v79, -v79, v100, v90
	v_div_fmas_f32 v79, v79, v91, v100
	v_div_fixup_f32 v78, v79, v78, 1.0
	v_pk_mul_f32 v[76:77], v[76:77], v[78:79] op_sel_hi:[1,0]
	v_and_b32_e32 v74, 0xffff0000, v74
	v_mul_f32_e32 v67, v67, v78
	v_pk_mul_f32 v[68:69], v[76:77], v[68:69]
	v_pk_mul_f32 v[70:71], v[76:77], v[70:71]
	v_pk_mul_f32 v[72:73], v[76:77], v[72:73]
	v_pk_mul_f32 v[78:79], v[76:77], v[80:81]
	v_pk_mul_f32 v[80:81], v[76:77], v[84:85]
	v_pk_mul_f32 v[74:75], v[76:77], v[74:75]
	v_pk_mul_f32 v[84:85], v[76:77], v[86:87]
	v_pk_mul_f32 v[76:77], v[76:77], v[88:89]
	v_fma_f32 v69, v67, v92, v69
	v_fma_f32 v71, v67, v93, v71
	v_fma_f32 v73, v67, v94, v73
	v_fma_f32 v79, v67, v95, v79
	v_fma_f32 v81, v67, v96, v81
	v_fma_f32 v75, v67, v97, v75
	v_fma_f32 v85, v67, v98, v85
	v_fma_f32 v67, v67, v99, v77
	v_add_f32_e32 v68, v68, v69
	v_add_f32_e32 v69, v70, v71
	v_add_f32_e32 v70, v72, v73
	v_add_f32_e32 v71, v78, v79
	v_add_f32_e32 v72, v80, v81
	v_add_f32_e32 v73, v74, v75
	v_add_f32_e32 v74, v84, v85
	v_add_f32_e32 v67, v76, v67
	v_cvt_pk_bf16_f32 v68, v68, v69
	v_cvt_pk_bf16_f32 v69, v70, v71
	v_cvt_pk_bf16_f32 v70, v72, v73
	v_cvt_pk_bf16_f32 v71, v74, v67
	global_store_dwordx4 v[82:83], v[68:71], off
	s_branch .LBB0_1296
